# norm row loops: 64-lane sums via DPP (quad_perm/half-mirror/mirror) + v_permlane16/32_swap instead of 6 ds_bpermute + lgkmcnt(0) steps each
# baseline (speedup 1.0000x reference)
; __device__ __forceinline__ float wave_sum(float v) {
; #pragma unroll
;     for (int o = 1; o < 64; o <<= 1) v += __shfl_xor(v, o);
;     return v;
; }
; template <bool HIN_BF16, bool HOUT_BF16>
; __device__ __forceinline__ void norm_rows(const bf16* __restrict__ Y, const void* Hin, void* H, const float* __restrict__ gpost, float* __restrict__ RSout, int gw, int NGW, int lane) {
;     ...
;             for (int j = 0; j < 4; ++j) y[j] = *(const v4u*)(Y + (size_t)m * DM + 512 * j + 8 * lane);
; #pragma unroll
;             for (int j = 0; j < 4; ++j)
; #pragma unroll
;                 for (int e = 0; e < 4; ++e) { const float a = bf_lo(y[j][e]), b = bf_hi(y[j][e]); ss += a * a + b * b; }
;             const float rs = 1.0f / sqrtf(wave_sum(ss) * (1.0f / DM) + RMS_EPS);
; #pragma unroll
;             for (int j = 0; j < 4; ++j) { const f32x4 g0 = *(const f32x4*)(gpost + 512 * j + 8 * lane), g1 = *(const f32x4*)(gpost + 512 * j + 8 * lane + 4);
;                 f32x4 a = {bf_lo(y[j][0]), bf_hi(y[j][0]), bf_lo(y[j][1]), bf_hi(y[j][1])}, b = {bf_lo(y[j][2]), bf_hi(y[j][2]), bf_lo(y[j][3]), bf_hi(y[j][3])};
;                 h[2 * j] = h[2 * j] + a * g0 * rs; h[2 * j + 1] = h[2 * j + 1] + b * g1 * rs; }
.Ln1_nopf:
	v_lshlrev_b32_e32 v74, 16, v42
	v_and_b32_e32 v75, 0xffff0000, v42
	v_lshlrev_b32_e32 v42, 16, v43
	v_and_b32_e32 v43, 0xffff0000, v43
	v_and_b32_e32 v77, 0xffff0000, v44
	v_lshlrev_b32_e32 v90, 16, v58
	v_and_b32_e32 v91, 0xffff0000, v58
	v_mul_f32_e32 v58, v75, v75
	v_mul_f32_e32 v94, v43, v43
	v_lshlrev_b32_e32 v76, 16, v44
	v_lshlrev_b32_e32 v44, 16, v45
	v_and_b32_e32 v45, 0xffff0000, v45
	v_mul_f32_e32 v95, v77, v77
	v_fmac_f32_e32 v58, v74, v74
	v_fmac_f32_e32 v94, v42, v42
	v_and_b32_e32 v79, 0xffff0000, v46
	v_mul_f32_e32 v96, v45, v45
	v_fmac_f32_e32 v95, v76, v76
	v_add_f32_e32 v58, v58, v94
	v_lshlrev_b32_e32 v78, 16, v46
	v_lshlrev_b32_e32 v46, 16, v47
	v_and_b32_e32 v47, 0xffff0000, v47
	v_mul_f32_e32 v97, v79, v79
	v_fmac_f32_e32 v96, v44, v44
	v_add_f32_e32 v58, v95, v58
	v_and_b32_e32 v81, 0xffff0000, v48
	v_mul_f32_e32 v98, v47, v47
	v_fmac_f32_e32 v97, v78, v78
	v_add_f32_e32 v58, v96, v58
	v_lshlrev_b32_e32 v80, 16, v48
	v_lshlrev_b32_e32 v48, 16, v49
	v_and_b32_e32 v49, 0xffff0000, v49
	v_mul_f32_e32 v99, v81, v81
	v_fmac_f32_e32 v98, v46, v46
	v_add_f32_e32 v58, v97, v58
	v_and_b32_e32 v83, 0xffff0000, v50
	v_mul_f32_e32 v100, v49, v49
	v_fmac_f32_e32 v99, v80, v80
	v_add_f32_e32 v58, v98, v58
	v_lshlrev_b32_e32 v82, 16, v50
	v_lshlrev_b32_e32 v50, 16, v51
	v_and_b32_e32 v51, 0xffff0000, v51
	v_mul_f32_e32 v101, v83, v83
	v_fmac_f32_e32 v100, v48, v48
	v_add_f32_e32 v58, v99, v58
	v_and_b32_e32 v85, 0xffff0000, v52
	v_mul_f32_e32 v102, v51, v51
	v_fmac_f32_e32 v101, v82, v82
	v_add_f32_e32 v58, v100, v58
	v_lshlrev_b32_e32 v84, 16, v52
	v_lshlrev_b32_e32 v52, 16, v53
	v_and_b32_e32 v53, 0xffff0000, v53
	v_mul_f32_e32 v103, v85, v85
	v_fmac_f32_e32 v102, v50, v50
	v_add_f32_e32 v58, v101, v58
	v_and_b32_e32 v87, 0xffff0000, v54
	v_mul_f32_e32 v104, v53, v53
	v_fmac_f32_e32 v103, v84, v84
	v_add_f32_e32 v58, v102, v58
	v_lshlrev_b32_e32 v86, 16, v54
	v_lshlrev_b32_e32 v54, 16, v55
	v_and_b32_e32 v55, 0xffff0000, v55
	v_mul_f32_e32 v105, v87, v87
	v_fmac_f32_e32 v104, v52, v52
	v_add_f32_e32 v58, v103, v58
	v_lshlrev_b32_e32 v89, 16, v57
	v_lshlrev_b32_e32 v88, 16, v56
	v_and_b32_e32 v57, 0xffff0000, v57
	v_and_b32_e32 v56, 0xffff0000, v56
	v_mul_f32_e32 v106, v55, v55
	v_fmac_f32_e32 v105, v86, v86
	v_add_f32_e32 v58, v104, v58
	v_pk_mul_f32 v[92:93], v[56:57], v[56:57]
	v_fmac_f32_e32 v106, v54, v54
	v_add_f32_e32 v58, v105, v58
	v_pk_fma_f32 v[92:93], v[88:89], v[88:89], v[92:93]
	v_add_f32_e32 v58, v106, v58
	v_add_f32_e32 v58, v92, v58
	v_add_f32_e32 v94, v93, v58
	s_nop 1
	v_mov_b32_dpp v95, v94 quad_perm:[1,0,3,2] row_mask:0xf bank_mask:0xf
	v_lshlrev_b32_e32 v58, 16, v59
	v_and_b32_e32 v59, 0xffff0000, v59
	v_pk_mul_f32 v[42:43], v[26:27], v[42:43]
	v_lshlrev_b32_e32 v92, 16, v60
	v_add_f32_e32 v96, v94, v95
	s_nop 1
	v_mov_b32_dpp v97, v96 quad_perm:[2,3,0,1] row_mask:0xf bank_mask:0xf
	v_and_b32_e32 v93, 0xffff0000, v60
	v_lshlrev_b32_e32 v60, 16, v61
	v_and_b32_e32 v61, 0xffff0000, v61
	v_pk_mul_f32 v[44:45], v[2:3], v[44:45]
	v_add_f32_e32 v98, v96, v97
	s_nop 1
	v_mov_b32_dpp v99, v98 row_half_mirror row_mask:0xf bank_mask:0xf
	v_lshlrev_b32_e32 v94, 16, v62
	v_and_b32_e32 v95, 0xffff0000, v62
	v_lshlrev_b32_e32 v62, 16, v63
	v_and_b32_e32 v63, 0xffff0000, v63
	v_add_f32_e32 v100, v98, v99
	s_nop 1
	v_mov_b32_dpp v101, v100 row_mirror row_mask:0xf bank_mask:0xf
	v_lshlrev_b32_e32 v96, 16, v64
	v_and_b32_e32 v97, 0xffff0000, v64
	v_lshlrev_b32_e32 v64, 16, v65
	v_and_b32_e32 v65, 0xffff0000, v65
	v_add_f32_e32 v102, v100, v101
	v_mov_b32_e32 v103, v102
	s_nop 1
	v_permlane16_swap_b32_e32 v102, v103
	v_lshlrev_b32_e32 v98, 16, v66
	v_and_b32_e32 v99, 0xffff0000, v66
	v_lshlrev_b32_e32 v66, 16, v67
	v_and_b32_e32 v67, 0xffff0000, v67
	v_add_f32_e32 v104, v102, v103
	v_mov_b32_e32 v105, v104
	s_nop 1
	v_permlane32_swap_b32_e32 v104, v105
	v_lshlrev_b32_e32 v102, 16, v70
	v_and_b32_e32 v103, 0xffff0000, v70
	v_lshlrev_b32_e32 v100, 16, v68
	v_and_b32_e32 v101, 0xffff0000, v68
	v_add_f32_e32 v70, v104, v105
	v_fmamk_f32 v70, v70, 0x3a000000, v226
	v_mul_f32_e32 v104, 0x4f800000, v70
	v_cmp_gt_f32_e32 vcc, s93, v70
	v_lshlrev_b32_e32 v68, 16, v69
	v_and_b32_e32 v69, 0xffff0000, v69
	v_cndmask_b32_e32 v105, v70, v104, vcc
	v_sqrt_f32_e32 v106, v105
	v_lshlrev_b32_e32 v70, 16, v71
	v_and_b32_e32 v71, 0xffff0000, v71
	v_pk_mul_f32 v[74:75], v[24:25], v[74:75]
	v_add_u32_e32 v107, -1, v106
	v_fma_f32 v109, -v107, v106, v105
	v_add_u32_e32 v108, 1, v106
	v_cmp_ge_f32_e64 s[46:47], 0, v109
	v_lshlrev_b32_e32 v104, 16, v72
	s_nop 0
	v_cndmask_b32_e64 v107, v106, v107, s[46:47]
	v_fma_f32 v106, -v108, v106, v105
	v_cmp_lt_f32_e64 s[46:47], 0, v106
	s_nop 1
	v_cndmask_b32_e64 v106, v107, v108, s[46:47]
	v_mul_f32_e32 v107, 0x37800000, v106
	v_cndmask_b32_e32 v106, v106, v107, vcc
	v_cmp_class_f32_e32 vcc, v105, v227
	s_nop 1
	v_cndmask_b32_e32 v106, v106, v105, vcc
	v_div_scale_f32 v107, s[10:11], v106, v106, 1.0
	v_rcp_f32_e32 v108, v107
	v_and_b32_e32 v105, 0xffff0000, v72
	v_lshlrev_b32_e32 v72, 16, v73
	v_and_b32_e32 v73, 0xffff0000, v73
	v_fma_f32 v109, -v107, v108, 1.0
	v_fmac_f32_e32 v108, v109, v108
	v_div_scale_f32 v109, vcc, 1.0, v106, 1.0
	v_mul_f32_e32 v110, v109, v108
	v_fma_f32 v111, -v107, v110, v109
	v_fmac_f32_e32 v110, v111, v108
	v_fma_f32 v107, -v107, v110, v109
	v_div_fmas_f32 v107, v107, v108, v110
	v_div_fixup_f32 v106, v107, v106, 1.0
	v_pk_fma_f32 v[58:59], v[42:43], v[106:107], v[58:59] op_sel_hi:[1,0,1]
	v_pk_mul_f32 v[42:43], v[0:1], v[76:77]
	v_pk_fma_f32 v[60:61], v[44:45], v[106:107], v[60:61] op_sel_hi:[1,0,1]
	v_pk_fma_f32 v[76:77], v[42:43], v[106:107], v[92:93] op_sel_hi:[1,0,1]
; __device__ __forceinline__ unsigned pk2(float lo, float hi) { return f2bf(lo) | (f2bf(hi) << 16); }
; template <bool HIN_BF16, bool HOUT_BF16>
; __device__ __forceinline__ void norm_rows(const bf16* __restrict__ Y, const void* Hin, void* H, const float* __restrict__ gpost, float* __restrict__ RSout, int gw, int NGW, int lane) {
;     ...
;             for (int j = 0; j < 4; ++j) { const f32x4 g0 = *(const f32x4*)(gpost + 512 * j + 8 * lane), g1 = *(const f32x4*)(gpost + 512 * j + 8 * lane + 4);
;                 f32x4 a = {bf_lo(y[j][0]), bf_hi(y[j][0]), bf_lo(y[j][1]), bf_hi(y[j][1])}, b = {bf_lo(y[j][2]), bf_hi(y[j][2]), bf_lo(y[j][3]), bf_hi(y[j][3])};
;                 h[2 * j] = h[2 * j] + a * g0 * rs; h[2 * j + 1] = h[2 * j + 1] + b * g1 * rs; }
;         }
;         if (HOUT_BF16) {
; #pragma unroll
;             for (int j = 0; j < 4; ++j) { v4u w; w.x = pk2(h[2 * j][0], h[2 * j][1]); w.y = pk2(h[2 * j][2], h[2 * j][3]); w.z = pk2(h[2 * j + 1][0], h[2 * j + 1][1]); w.w = pk2(h[2 * j + 1][2], h[2 * j + 1][3]);
;                 *(v4u*)((bf16*)H + (size_t)m * DM + 512 * j + 8 * lane) = w; }
;         } else { float* ho = (float*)H + (size_t)m * DM + 8 * lane;
; #pragma unroll
;             for (int j = 0; j < 4; ++j) { *(f32x4*)(ho + 512 * j) = h[2 * j]; *(f32x4*)(ho + 512 * j + 4) = h[2 * j + 1]; } }
;         if (RSout) {
;             float ss = 0.f;
; #pragma unroll
;             for (int j = 0; j < 8; ++j) ss += (h[j][0] * h[j][0] + h[j][1] * h[j][1]) + (h[j][2] * h[j][2] + h[j][3] * h[j][3]);
;             const float rs = 1.0f / sqrtf(wave_sum(ss) * (1.0f / DM) + RMS_EPS);
	v_pk_mul_f32 v[42:43], v[4:5], v[78:79]
	v_pk_mul_f32 v[44:45], v[6:7], v[46:47]
	v_pk_fma_f32 v[74:75], v[74:75], v[106:107], v[90:91] op_sel_hi:[1,0,1]
	v_pk_fma_f32 v[46:47], v[44:45], v[106:107], v[62:63] op_sel_hi:[1,0,1]
	v_pk_fma_f32 v[62:63], v[42:43], v[106:107], v[94:95] op_sel_hi:[1,0,1]
	v_pk_mul_f32 v[42:43], v[8:9], v[80:81]
	v_pk_mul_f32 v[44:45], v[10:11], v[48:49]
	v_bfe_u32 v78, v61, 16, 1
	v_pk_fma_f32 v[48:49], v[44:45], v[106:107], v[64:65] op_sel_hi:[1,0,1]
	v_pk_fma_f32 v[64:65], v[42:43], v[106:107], v[96:97] op_sel_hi:[1,0,1]
	v_pk_mul_f32 v[42:43], v[16:17], v[82:83]
	v_pk_mul_f32 v[44:45], v[18:19], v[50:51]
	v_add3_u32 v78, v61, v78, s56
	v_pk_fma_f32 v[50:51], v[44:45], v[106:107], v[66:67] op_sel_hi:[1,0,1]
	v_pk_fma_f32 v[66:67], v[42:43], v[106:107], v[98:99] op_sel_hi:[1,0,1]
	v_pk_mul_f32 v[42:43], v[12:13], v[84:85]
	v_pk_mul_f32 v[44:45], v[14:15], v[52:53]
	s_nop 0
	v_pk_fma_f32 v[52:53], v[44:45], v[106:107], v[68:69] op_sel_hi:[1,0,1]
	v_pk_fma_f32 v[68:69], v[42:43], v[106:107], v[100:101] op_sel_hi:[1,0,1]
	v_pk_mul_f32 v[42:43], v[20:21], v[86:87]
	v_pk_mul_f32 v[44:45], v[22:23], v[54:55]
	s_nop 0
	v_pk_fma_f32 v[54:55], v[44:45], v[106:107], v[70:71] op_sel_hi:[1,0,1]
	v_pk_fma_f32 v[70:71], v[42:43], v[106:107], v[102:103] op_sel_hi:[1,0,1]
	v_mov_b32_e32 v42, v88
	v_mov_b32_e32 v43, v56
	v_mov_b32_e32 v56, v89
	v_pk_mul_f32 v[42:43], v[28:29], v[42:43]
	v_pk_mul_f32 v[44:45], v[30:31], v[56:57]
	s_nop 0
	v_pk_fma_f32 v[56:57], v[44:45], v[106:107], v[72:73] op_sel_hi:[1,0,1]
	v_pk_fma_f32 v[72:73], v[42:43], v[106:107], v[104:105] op_sel_hi:[1,0,1]
	v_bfe_u32 v42, v74, 16, 1
	v_add3_u32 v42, v74, v42, s56
	v_bfe_u32 v43, v75, 16, 1
	v_lshrrev_b32_e32 v42, 16, v42
	v_add3_u32 v43, v75, v43, s56
	v_and_or_b32 v42, v43, s82, v42
	v_bfe_u32 v43, v58, 16, 1
	v_add3_u32 v43, v58, v43, s56
	v_bfe_u32 v44, v59, 16, 1
	v_lshrrev_b32_e32 v43, 16, v43
	v_add3_u32 v44, v59, v44, s56
	v_and_or_b32 v43, v44, s82, v43
	v_bfe_u32 v44, v76, 16, 1
	v_add3_u32 v44, v76, v44, s56
	v_bfe_u32 v45, v77, 16, 1
	v_lshrrev_b32_e32 v44, 16, v44
	v_add3_u32 v45, v77, v45, s56
	v_and_or_b32 v44, v45, s82, v44
	v_bfe_u32 v45, v60, 16, 1
	v_add3_u32 v45, v60, v45, s56
	v_lshrrev_b32_e32 v45, 16, v45
	v_and_or_b32 v45, v78, s82, v45
	global_store_dwordx4 v[34:35], v[42:45], off
	v_bfe_u32 v78, v49, 16, 1
	v_add3_u32 v78, v49, v78, s56
	v_bfe_u32 v42, v62, 16, 1
	v_add3_u32 v42, v62, v42, s56
	v_bfe_u32 v43, v63, 16, 1
	v_lshrrev_b32_e32 v42, 16, v42
	v_add3_u32 v43, v63, v43, s56
	v_and_or_b32 v42, v43, s82, v42
	v_bfe_u32 v43, v46, 16, 1
	v_add3_u32 v43, v46, v43, s56
	v_bfe_u32 v44, v47, 16, 1
	v_lshrrev_b32_e32 v43, 16, v43
	v_add3_u32 v44, v47, v44, s56
	v_and_or_b32 v43, v44, s82, v43
	v_bfe_u32 v44, v64, 16, 1
	v_add3_u32 v44, v64, v44, s56
	v_bfe_u32 v45, v65, 16, 1
	v_lshrrev_b32_e32 v44, 16, v44
	v_add3_u32 v45, v65, v45, s56
	v_and_or_b32 v44, v45, s82, v44
	v_bfe_u32 v45, v48, 16, 1
	v_add3_u32 v45, v48, v45, s56
	v_lshrrev_b32_e32 v45, 16, v45
	v_and_or_b32 v45, v78, s82, v45
	global_store_dwordx4 v[34:35], v[42:45], off offset:1024
	v_bfe_u32 v78, v53, 16, 1
	v_add3_u32 v78, v53, v78, s56
	v_bfe_u32 v42, v66, 16, 1
	v_add3_u32 v42, v66, v42, s56
	v_bfe_u32 v43, v67, 16, 1
	v_lshrrev_b32_e32 v42, 16, v42
	v_add3_u32 v43, v67, v43, s56
	v_and_or_b32 v42, v43, s82, v42
	v_bfe_u32 v43, v50, 16, 1
	v_add3_u32 v43, v50, v43, s56
	v_bfe_u32 v44, v51, 16, 1
	v_lshrrev_b32_e32 v43, 16, v43
	v_add3_u32 v44, v51, v44, s56
	v_and_or_b32 v43, v44, s82, v43
	v_bfe_u32 v44, v68, 16, 1
	v_add3_u32 v44, v68, v44, s56
	v_bfe_u32 v45, v69, 16, 1
	v_lshrrev_b32_e32 v44, 16, v44
	v_add3_u32 v45, v69, v45, s56
	v_and_or_b32 v44, v45, s82, v44
	v_bfe_u32 v45, v52, 16, 1
	v_add3_u32 v45, v52, v45, s56
	v_lshrrev_b32_e32 v45, 16, v45
	v_and_or_b32 v45, v78, s82, v45
	global_store_dwordx4 v[34:35], v[42:45], off offset:2048
	s_nop 1
	v_mul_f32_e32 v43, v75, v75
	v_mul_f32_e32 v44, v59, v59
	v_fmac_f32_e32 v43, v74, v74
	v_fmac_f32_e32 v44, v58, v58
	v_add_f32_e32 v43, v43, v44
	v_mul_f32_e32 v44, v77, v77
	v_mul_f32_e32 v45, v61, v61
	v_fmac_f32_e32 v44, v76, v76
	v_fmac_f32_e32 v45, v60, v60
	v_add_f32_e32 v44, v44, v45
	v_add_f32_e32 v43, v43, v44
	v_mul_f32_e32 v44, v63, v63
	v_mul_f32_e32 v45, v47, v47
	v_fmac_f32_e32 v44, v62, v62
	v_fmac_f32_e32 v45, v46, v46
	v_add_f32_e32 v44, v44, v45
	v_add_f32_e32 v43, v44, v43
	v_mul_f32_e32 v44, v65, v65
	v_mul_f32_e32 v45, v49, v49
	v_fmac_f32_e32 v44, v64, v64
	v_fmac_f32_e32 v45, v48, v48
	v_add_f32_e32 v44, v44, v45
	v_add_f32_e32 v43, v44, v43
	v_mul_f32_e32 v44, v67, v67
	v_mul_f32_e32 v45, v51, v51
	v_fmac_f32_e32 v44, v66, v66
	v_fmac_f32_e32 v45, v50, v50
	v_add_f32_e32 v44, v44, v45
	v_add_f32_e32 v43, v44, v43
	v_mul_f32_e32 v44, v69, v69
	v_mul_f32_e32 v45, v53, v53
	v_fmac_f32_e32 v44, v68, v68
	v_fmac_f32_e32 v45, v52, v52
	v_add_f32_e32 v44, v44, v45
	v_add_f32_e32 v43, v44, v43
	v_mul_f32_e32 v44, v71, v71
	v_mul_f32_e32 v45, v55, v55
	v_fmac_f32_e32 v44, v70, v70
	v_fmac_f32_e32 v45, v54, v54
	v_add_f32_e32 v44, v44, v45
	v_add_f32_e32 v43, v44, v43
	v_mul_f32_e32 v44, v73, v73
	v_mul_f32_e32 v45, v57, v57
	v_fmac_f32_e32 v44, v72, v72
	v_fmac_f32_e32 v45, v56, v56
	v_add_f32_e32 v44, v44, v45
	v_add_f32_e32 v43, v44, v43
	s_nop 1
	v_mov_b32_dpp v44, v43 quad_perm:[1,0,3,2] row_mask:0xf bank_mask:0xf
	v_bfe_u32 v42, v70, 16, 1
	v_add3_u32 v42, v70, v42, s56
	v_bfe_u32 v45, v71, 16, 1
	v_lshrrev_b32_e32 v42, 16, v42
	v_add_f32_e32 v43, v43, v44
	s_nop 1
	v_mov_b32_dpp v46, v43 quad_perm:[2,3,0,1] row_mask:0xf bank_mask:0xf
	v_add3_u32 v45, v71, v45, s56
	v_and_or_b32 v44, v45, s82, v42
	v_bfe_u32 v42, v54, 16, 1
	v_add3_u32 v42, v54, v42, s56
	v_add_f32_e32 v43, v43, v46
	s_nop 1
	v_mov_b32_dpp v46, v43 row_half_mirror row_mask:0xf bank_mask:0xf
	v_bfe_u32 v45, v55, 16, 1
	v_lshrrev_b32_e32 v42, 16, v42
	v_add3_u32 v45, v55, v45, s56
	v_and_or_b32 v45, v45, s82, v42
	v_add_f32_e32 v43, v43, v46
	s_nop 1
	v_mov_b32_dpp v46, v43 row_mirror row_mask:0xf bank_mask:0xf
	v_bfe_u32 v42, v72, 16, 1
	v_add3_u32 v42, v72, v42, s56
	v_bfe_u32 v47, v73, 16, 1
	v_lshrrev_b32_e32 v42, 16, v42
	v_add_f32_e32 v43, v43, v46
	v_mov_b32_e32 v48, v43
	s_nop 1
	v_permlane16_swap_b32_e32 v43, v48
	v_add3_u32 v47, v73, v47, s56
	v_and_or_b32 v46, v47, s82, v42
	v_bfe_u32 v42, v56, 16, 1
	v_add3_u32 v42, v56, v42, s56
	v_lshrrev_b32_e32 v47, 16, v42
	v_add_f32_e32 v42, v43, v48
	v_mov_b32_e32 v43, v42
	s_nop 1
	v_permlane32_swap_b32_e32 v42, v43
	v_bfe_u32 v48, v57, 16, 1
	v_add3_u32 v48, v57, v48, s56
	v_and_or_b32 v47, v48, s82, v47
	global_store_dwordx4 v[34:35], v[44:47], off offset:3072
	s_and_saveexec_b64 s[10:11], s[42:43]
	s_cbranch_execz .LBB0_512
; template <bool HIN_BF16, bool HOUT_BF16>
; __device__ __forceinline__ void norm_rows(const bf16* __restrict__ Y, const void* Hin, void* H, const float* __restrict__ gpost, float* __restrict__ RSout, int gw, int NGW, int lane) {
;     ...
;             const float rs = 1.0f / sqrtf(wave_sum(ss) * (1.0f / DM) + RMS_EPS);
;             if (lane == 0) RSout[m] = rs;
	v_add_f32_e32 v34, v42, v43
	v_fmamk_f32 v34, v34, 0x3a000000, v226
	v_mul_f32_e32 v35, 0x4f800000, v34
	v_cmp_gt_f32_e32 vcc, s93, v34
	s_nop 1
	v_cndmask_b32_e32 v34, v34, v35, vcc
	v_sqrt_f32_e32 v35, v34
	s_nop 0
	v_add_u32_e32 v42, -1, v35
	v_fma_f32 v44, -v42, v35, v34
	v_add_u32_e32 v43, 1, v35
	v_cmp_ge_f32_e64 s[46:47], 0, v44
	s_nop 1
	v_cndmask_b32_e64 v42, v35, v42, s[46:47]
	v_fma_f32 v35, -v43, v35, v34
	v_cmp_lt_f32_e64 s[46:47], 0, v35
	s_nop 1
	v_cndmask_b32_e64 v35, v42, v43, s[46:47]
	v_mul_f32_e32 v42, 0x37800000, v35
	v_cndmask_b32_e32 v35, v35, v42, vcc
	v_cmp_class_f32_e32 vcc, v34, v227
	s_nop 1
	v_cndmask_b32_e32 v34, v35, v34, vcc
	v_div_scale_f32 v35, s[20:21], v34, v34, 1.0
	v_rcp_f32_e32 v42, v35
	s_add_u32 s20, s6, s4
	s_addc_u32 s21, s7, s5
	v_fma_f32 v43, -v35, v42, 1.0
	v_fmac_f32_e32 v42, v43, v42
	v_div_scale_f32 v43, vcc, 1.0, v34, 1.0
	v_mul_f32_e32 v44, v43, v42
	v_fma_f32 v45, -v35, v44, v43
	v_fmac_f32_e32 v44, v45, v42
	v_fma_f32 v35, -v35, v44, v43
	v_div_fmas_f32 v35, v35, v42, v44
	v_div_fixup_f32 v34, v35, v34, 1.0
	global_store_dword v205, v34, s[20:21]
	s_branch .LBB0_512

; __device__ __forceinline__ float wave_sum(float v) {
; #pragma unroll
;     for (int o = 1; o < 64; o <<= 1) v += __shfl_xor(v, o);
;     return v;
; }
; template <bool HIN_BF16, bool HOUT_BF16>
; __device__ __forceinline__ void norm_rows(const bf16* __restrict__ Y, const void* Hin, void* H, const float* __restrict__ gpost, float* __restrict__ RSout, int gw, int NGW, int lane) {
;     ...
;             for (int j = 0; j < 4; ++j) y[j] = *(const v4u*)(Y + (size_t)m * DM + 512 * j + 8 * lane);
; #pragma unroll
;             for (int j = 0; j < 4; ++j)
; #pragma unroll
;                 for (int e = 0; e < 4; ++e) { const float a = bf_lo(y[j][e]), b = bf_hi(y[j][e]); ss += a * a + b * b; }
;             const float rs = 1.0f / sqrtf(wave_sum(ss) * (1.0f / DM) + RMS_EPS);
; #pragma unroll
;             for (int j = 0; j < 4; ++j) { const f32x4 g0 = *(const f32x4*)(gpost + 512 * j + 8 * lane), g1 = *(const f32x4*)(gpost + 512 * j + 8 * lane + 4);
;                 f32x4 a = {bf_lo(y[j][0]), bf_hi(y[j][0]), bf_lo(y[j][1]), bf_hi(y[j][1])}, b = {bf_lo(y[j][2]), bf_hi(y[j][2]), bf_lo(y[j][3]), bf_hi(y[j][3])};
;                 h[2 * j] = h[2 * j] + a * g0 * rs; h[2 * j + 1] = h[2 * j + 1] + b * g1 * rs; }
.Ln2_nopf:
	v_lshlrev_b32_e32 v76, 16, v44
	v_and_b32_e32 v77, 0xffff0000, v44
	v_lshlrev_b32_e32 v44, 16, v45
	v_and_b32_e32 v45, 0xffff0000, v45
	v_and_b32_e32 v79, 0xffff0000, v46
	v_lshlrev_b32_e32 v92, 16, v60
	v_and_b32_e32 v93, 0xffff0000, v60
	v_mul_f32_e32 v43, v77, v77
	v_mul_f32_e32 v60, v45, v45
	v_lshlrev_b32_e32 v78, 16, v46
	v_lshlrev_b32_e32 v46, 16, v47
	v_and_b32_e32 v47, 0xffff0000, v47
	v_mul_f32_e32 v96, v79, v79
	v_fmac_f32_e32 v43, v76, v76
	v_fmac_f32_e32 v60, v44, v44
	v_and_b32_e32 v81, 0xffff0000, v48
	v_mul_f32_e32 v97, v47, v47
	v_fmac_f32_e32 v96, v78, v78
	v_add_f32_e32 v43, v43, v60
	v_lshlrev_b32_e32 v80, 16, v48
	v_lshlrev_b32_e32 v48, 16, v49
	v_and_b32_e32 v49, 0xffff0000, v49
	v_mul_f32_e32 v98, v81, v81
	v_fmac_f32_e32 v97, v46, v46
	v_add_f32_e32 v43, v96, v43
	v_and_b32_e32 v83, 0xffff0000, v50
	v_mul_f32_e32 v99, v49, v49
	v_fmac_f32_e32 v98, v80, v80
	v_add_f32_e32 v43, v97, v43
	v_lshlrev_b32_e32 v82, 16, v50
	v_lshlrev_b32_e32 v50, 16, v51
	v_and_b32_e32 v51, 0xffff0000, v51
	v_mul_f32_e32 v100, v83, v83
	v_fmac_f32_e32 v99, v48, v48
	v_add_f32_e32 v43, v98, v43
	v_and_b32_e32 v85, 0xffff0000, v52
	v_mul_f32_e32 v101, v51, v51
	v_fmac_f32_e32 v100, v82, v82
	v_add_f32_e32 v43, v99, v43
	v_lshlrev_b32_e32 v84, 16, v52
	v_lshlrev_b32_e32 v52, 16, v53
	v_and_b32_e32 v53, 0xffff0000, v53
	v_mul_f32_e32 v102, v85, v85
	v_fmac_f32_e32 v101, v50, v50
	v_add_f32_e32 v43, v100, v43
	v_and_b32_e32 v87, 0xffff0000, v54
	v_mul_f32_e32 v103, v53, v53
	v_fmac_f32_e32 v102, v84, v84
	v_add_f32_e32 v43, v101, v43
	v_lshlrev_b32_e32 v86, 16, v54
	v_lshlrev_b32_e32 v54, 16, v55
	v_and_b32_e32 v55, 0xffff0000, v55
	v_mul_f32_e32 v104, v87, v87
	v_fmac_f32_e32 v103, v52, v52
	v_add_f32_e32 v43, v102, v43
	v_and_b32_e32 v89, 0xffff0000, v56
	v_mul_f32_e32 v105, v55, v55
	v_fmac_f32_e32 v104, v86, v86
	v_add_f32_e32 v43, v103, v43
	v_lshlrev_b32_e32 v88, 16, v56
	v_lshlrev_b32_e32 v56, 16, v57
	v_and_b32_e32 v57, 0xffff0000, v57
	v_mul_f32_e32 v106, v89, v89
	v_fmac_f32_e32 v105, v54, v54
	v_add_f32_e32 v43, v104, v43
	v_lshlrev_b32_e32 v91, 16, v59
	v_lshlrev_b32_e32 v90, 16, v58
	v_and_b32_e32 v59, 0xffff0000, v59
	v_and_b32_e32 v58, 0xffff0000, v58
	v_mul_f32_e32 v107, v57, v57
	v_fmac_f32_e32 v106, v88, v88
	v_add_f32_e32 v43, v105, v43
	v_pk_mul_f32 v[94:95], v[58:59], v[58:59]
	v_fmac_f32_e32 v107, v56, v56
	v_add_f32_e32 v43, v106, v43
	v_pk_fma_f32 v[94:95], v[90:91], v[90:91], v[94:95]
	v_add_f32_e32 v43, v107, v43
	v_add_f32_e32 v43, v94, v43
	v_add_f32_e32 v43, v95, v43
	s_nop 1
	v_mov_b32_dpp v96, v43 quad_perm:[1,0,3,2] row_mask:0xf bank_mask:0xf
	v_and_b32_e32 v105, 0xffff0000, v72
	v_lshlrev_b32_e32 v60, 16, v61
	v_and_b32_e32 v61, 0xffff0000, v61
	v_pk_mul_f32 v[44:45], v[26:27], v[44:45]
	v_add_f32_e32 v43, v43, v96
	s_nop 1
	v_mov_b32_dpp v98, v43 quad_perm:[2,3,0,1] row_mask:0xf bank_mask:0xf
	v_lshlrev_b32_e32 v94, 16, v62
	v_and_b32_e32 v95, 0xffff0000, v62
	v_lshlrev_b32_e32 v62, 16, v63
	v_and_b32_e32 v63, 0xffff0000, v63
	v_add_f32_e32 v43, v43, v98
	s_nop 1
	v_mov_b32_dpp v100, v43 row_half_mirror row_mask:0xf bank_mask:0xf
	v_pk_mul_f32 v[46:47], v[2:3], v[46:47]
	v_lshlrev_b32_e32 v96, 16, v64
	v_and_b32_e32 v97, 0xffff0000, v64
	v_lshlrev_b32_e32 v64, 16, v65
	v_add_f32_e32 v43, v43, v100
	s_nop 1
	v_mov_b32_dpp v102, v43 row_mirror row_mask:0xf bank_mask:0xf
	v_and_b32_e32 v65, 0xffff0000, v65
	v_lshlrev_b32_e32 v98, 16, v66
	v_and_b32_e32 v99, 0xffff0000, v66
	v_lshlrev_b32_e32 v66, 16, v67
	v_add_f32_e32 v43, v43, v102
	v_mov_b32_e32 v104, v43
	s_nop 1
	v_permlane16_swap_b32_e32 v43, v104
	v_and_b32_e32 v67, 0xffff0000, v67
	v_lshlrev_b32_e32 v100, 16, v68
	v_and_b32_e32 v101, 0xffff0000, v68
	v_lshlrev_b32_e32 v68, 16, v69
	v_add_f32_e32 v43, v43, v104
	v_mov_b32_e32 v106, v43
	s_nop 1
	v_permlane32_swap_b32_e32 v43, v106
	v_lshlrev_b32_e32 v104, 16, v72
	v_and_b32_e32 v69, 0xffff0000, v69
	v_lshlrev_b32_e32 v102, 16, v70
	v_and_b32_e32 v103, 0xffff0000, v70
	v_add_f32_e32 v43, v43, v106
	v_fmamk_f32 v43, v43, 0x3a000000, v226
	v_mul_f32_e32 v72, 0x4f800000, v43
	v_cmp_gt_f32_e32 vcc, s93, v43
	v_lshlrev_b32_e32 v70, 16, v71
	v_and_b32_e32 v71, 0xffff0000, v71
	v_cndmask_b32_e32 v43, v43, v72, vcc
	v_sqrt_f32_e32 v107, v43
	v_lshlrev_b32_e32 v72, 16, v73
	v_and_b32_e32 v73, 0xffff0000, v73
	v_pk_mul_f32 v[76:77], v[24:25], v[76:77]
	v_add_u32_e32 v108, -1, v107
	v_fma_f32 v110, -v108, v107, v43
	v_add_u32_e32 v109, 1, v107
	v_cmp_ge_f32_e64 s[42:43], 0, v110
	v_lshlrev_b32_e32 v106, 16, v74
	s_nop 0
	v_cndmask_b32_e64 v108, v107, v108, s[42:43]
	v_fma_f32 v107, -v109, v107, v43
	v_cmp_lt_f32_e64 s[42:43], 0, v107
	s_nop 1
	v_cndmask_b32_e64 v107, v108, v109, s[42:43]
	v_mul_f32_e32 v108, 0x37800000, v107
	v_cndmask_b32_e32 v107, v107, v108, vcc
	v_cmp_class_f32_e32 vcc, v43, v227
	s_nop 1
	v_cndmask_b32_e32 v43, v107, v43, vcc
	v_div_scale_f32 v108, s[10:11], v43, v43, 1.0
	v_rcp_f32_e32 v109, v108
	v_and_b32_e32 v107, 0xffff0000, v74
	v_lshlrev_b32_e32 v74, 16, v75
	v_and_b32_e32 v75, 0xffff0000, v75
	v_fma_f32 v110, -v108, v109, 1.0
	v_fmac_f32_e32 v109, v110, v109
	v_div_scale_f32 v110, vcc, 1.0, v43, 1.0
	v_mul_f32_e32 v111, v110, v109
	v_fma_f32 v112, -v108, v111, v110
	v_fmac_f32_e32 v111, v112, v109
	v_fma_f32 v108, -v108, v111, v110
	v_div_fmas_f32 v108, v108, v109, v111
	v_div_fixup_f32 v108, v108, v43, 1.0
	v_pk_fma_f32 v[60:61], v[44:45], v[108:109], v[60:61] op_sel_hi:[1,0,1]
	v_pk_mul_f32 v[44:45], v[0:1], v[78:79]
	v_pk_fma_f32 v[62:63], v[46:47], v[108:109], v[62:63] op_sel_hi:[1,0,1]
	v_pk_fma_f32 v[78:79], v[44:45], v[108:109], v[94:95] op_sel_hi:[1,0,1]
; __device__ __forceinline__ unsigned pk2(float lo, float hi) { return f2bf(lo) | (f2bf(hi) << 16); }
; template <bool HIN_BF16, bool HOUT_BF16>
; __device__ __forceinline__ void norm_rows(const bf16* __restrict__ Y, const void* Hin, void* H, const float* __restrict__ gpost, float* __restrict__ RSout, int gw, int NGW, int lane) {
;     ...
;             for (int j = 0; j < 4; ++j) { const f32x4 g0 = *(const f32x4*)(gpost + 512 * j + 8 * lane), g1 = *(const f32x4*)(gpost + 512 * j + 8 * lane + 4);
;                 f32x4 a = {bf_lo(y[j][0]), bf_hi(y[j][0]), bf_lo(y[j][1]), bf_hi(y[j][1])}, b = {bf_lo(y[j][2]), bf_hi(y[j][2]), bf_lo(y[j][3]), bf_hi(y[j][3])};
;                 h[2 * j] = h[2 * j] + a * g0 * rs; h[2 * j + 1] = h[2 * j + 1] + b * g1 * rs; }
;         }
;         if (HOUT_BF16) {
; #pragma unroll
;             for (int j = 0; j < 4; ++j) { v4u w; w.x = pk2(h[2 * j][0], h[2 * j][1]); w.y = pk2(h[2 * j][2], h[2 * j][3]); w.z = pk2(h[2 * j + 1][0], h[2 * j + 1][1]); w.w = pk2(h[2 * j + 1][2], h[2 * j + 1][3]);
;                 *(v4u*)((bf16*)H + (size_t)m * DM + 512 * j + 8 * lane) = w; }
;         } else { float* ho = (float*)H + (size_t)m * DM + 8 * lane;
; #pragma unroll
;             for (int j = 0; j < 4; ++j) { *(f32x4*)(ho + 512 * j) = h[2 * j]; *(f32x4*)(ho + 512 * j + 4) = h[2 * j + 1]; } }
;         if (RSout) {
;             float ss = 0.f;
; #pragma unroll
;             for (int j = 0; j < 8; ++j) ss += (h[j][0] * h[j][0] + h[j][1] * h[j][1]) + (h[j][2] * h[j][2] + h[j][3] * h[j][3]);
;             const float rs = 1.0f / sqrtf(wave_sum(ss) * (1.0f / DM) + RMS_EPS);
	v_pk_mul_f32 v[44:45], v[4:5], v[80:81]
	v_pk_mul_f32 v[46:47], v[6:7], v[48:49]
	v_pk_fma_f32 v[76:77], v[76:77], v[108:109], v[92:93] op_sel_hi:[1,0,1]
	v_pk_fma_f32 v[48:49], v[46:47], v[108:109], v[64:65] op_sel_hi:[1,0,1]
	v_pk_fma_f32 v[64:65], v[44:45], v[108:109], v[96:97] op_sel_hi:[1,0,1]
	v_pk_mul_f32 v[44:45], v[8:9], v[82:83]
	v_pk_mul_f32 v[46:47], v[10:11], v[50:51]
	v_bfe_u32 v43, v76, 16, 1
	v_pk_fma_f32 v[50:51], v[46:47], v[108:109], v[66:67] op_sel_hi:[1,0,1]
	v_pk_fma_f32 v[66:67], v[44:45], v[108:109], v[98:99] op_sel_hi:[1,0,1]
	v_pk_mul_f32 v[44:45], v[16:17], v[84:85]
	v_pk_mul_f32 v[46:47], v[18:19], v[52:53]
	v_add3_u32 v43, v76, v43, s56
	v_pk_fma_f32 v[52:53], v[46:47], v[108:109], v[68:69] op_sel_hi:[1,0,1]
	v_pk_fma_f32 v[68:69], v[44:45], v[108:109], v[100:101] op_sel_hi:[1,0,1]
	v_pk_mul_f32 v[44:45], v[12:13], v[86:87]
	v_pk_mul_f32 v[46:47], v[14:15], v[54:55]
	v_lshrrev_b32_e32 v43, 16, v43
	v_pk_fma_f32 v[54:55], v[46:47], v[108:109], v[70:71] op_sel_hi:[1,0,1]
	v_pk_fma_f32 v[70:71], v[44:45], v[108:109], v[102:103] op_sel_hi:[1,0,1]
	v_pk_mul_f32 v[44:45], v[20:21], v[88:89]
	v_pk_mul_f32 v[46:47], v[22:23], v[56:57]
	s_nop 0
	v_pk_fma_f32 v[56:57], v[46:47], v[108:109], v[72:73] op_sel_hi:[1,0,1]
	v_pk_fma_f32 v[72:73], v[44:45], v[108:109], v[104:105] op_sel_hi:[1,0,1]
	v_mov_b32_e32 v44, v90
	v_mov_b32_e32 v45, v58
	v_mov_b32_e32 v58, v91
	v_pk_mul_f32 v[44:45], v[28:29], v[44:45]
	v_pk_mul_f32 v[46:47], v[30:31], v[58:59]
	s_nop 0
	v_pk_fma_f32 v[58:59], v[46:47], v[108:109], v[74:75] op_sel_hi:[1,0,1]
	v_pk_fma_f32 v[74:75], v[44:45], v[108:109], v[106:107] op_sel_hi:[1,0,1]
	v_bfe_u32 v44, v77, 16, 1
	v_add3_u32 v44, v77, v44, s56
	v_and_or_b32 v44, v44, s82, v43
	v_bfe_u32 v43, v60, 16, 1
	v_add3_u32 v43, v60, v43, s56
	v_bfe_u32 v45, v61, 16, 1
	v_lshrrev_b32_e32 v43, 16, v43
	v_add3_u32 v45, v61, v45, s56
	v_and_or_b32 v45, v45, s82, v43
	v_bfe_u32 v43, v78, 16, 1
	v_add3_u32 v43, v78, v43, s56
	v_bfe_u32 v46, v79, 16, 1
	v_lshrrev_b32_e32 v43, 16, v43
	v_add3_u32 v46, v79, v46, s56
	v_and_or_b32 v46, v46, s82, v43
	v_bfe_u32 v43, v62, 16, 1
	v_add3_u32 v43, v62, v43, s56
	v_bfe_u32 v47, v63, 16, 1
	v_lshrrev_b32_e32 v43, 16, v43
	v_add3_u32 v47, v63, v47, s56
	v_and_or_b32 v47, v47, s82, v43
	v_bfe_u32 v43, v64, 16, 1
	global_store_dwordx4 v[34:35], v[44:47], off
	v_add3_u32 v43, v64, v43, s56
	v_lshrrev_b32_e32 v43, 16, v43
	v_bfe_u32 v44, v65, 16, 1
	v_add3_u32 v44, v65, v44, s56
	v_and_or_b32 v44, v44, s82, v43
	v_bfe_u32 v43, v48, 16, 1
	v_add3_u32 v43, v48, v43, s56
	v_bfe_u32 v45, v49, 16, 1
	v_lshrrev_b32_e32 v43, 16, v43
	v_add3_u32 v45, v49, v45, s56
	v_and_or_b32 v45, v45, s82, v43
	v_bfe_u32 v43, v66, 16, 1
	v_add3_u32 v43, v66, v43, s56
	v_bfe_u32 v46, v67, 16, 1
	v_lshrrev_b32_e32 v43, 16, v43
	v_add3_u32 v46, v67, v46, s56
	v_and_or_b32 v46, v46, s82, v43
	v_bfe_u32 v43, v50, 16, 1
	v_add3_u32 v43, v50, v43, s56
	v_bfe_u32 v47, v51, 16, 1
	v_lshrrev_b32_e32 v43, 16, v43
	v_add3_u32 v47, v51, v47, s56
	v_and_or_b32 v47, v47, s82, v43
	v_bfe_u32 v43, v68, 16, 1
	global_store_dwordx4 v[34:35], v[44:47], off offset:1024
	v_add3_u32 v43, v68, v43, s56
	v_lshrrev_b32_e32 v43, 16, v43
	v_bfe_u32 v44, v69, 16, 1
	v_add3_u32 v44, v69, v44, s56
	v_and_or_b32 v44, v44, s82, v43
	v_bfe_u32 v43, v52, 16, 1
	v_add3_u32 v43, v52, v43, s56
	v_bfe_u32 v45, v53, 16, 1
	v_lshrrev_b32_e32 v43, 16, v43
	v_add3_u32 v45, v53, v45, s56
	v_and_or_b32 v45, v45, s82, v43
	v_bfe_u32 v43, v70, 16, 1
	v_add3_u32 v43, v70, v43, s56
	v_bfe_u32 v46, v71, 16, 1
	v_lshrrev_b32_e32 v43, 16, v43
	v_add3_u32 v46, v71, v46, s56
	v_and_or_b32 v46, v46, s82, v43
	v_bfe_u32 v43, v54, 16, 1
	v_add3_u32 v43, v54, v43, s56
	v_bfe_u32 v47, v55, 16, 1
	v_lshrrev_b32_e32 v43, 16, v43
	v_add3_u32 v47, v55, v47, s56
	v_and_or_b32 v47, v47, s82, v43
	global_store_dwordx4 v[34:35], v[44:47], off offset:2048
	v_bfe_u32 v43, v72, 16, 1
	v_add3_u32 v43, v72, v43, s56
	v_mul_f32_e32 v44, v77, v77
	v_mul_f32_e32 v45, v61, v61
	v_fmac_f32_e32 v44, v76, v76
	v_fmac_f32_e32 v45, v60, v60
	v_add_f32_e32 v44, v44, v45
	v_mul_f32_e32 v45, v79, v79
	v_mul_f32_e32 v46, v63, v63
	v_fmac_f32_e32 v45, v78, v78
	v_fmac_f32_e32 v46, v62, v62
	v_add_f32_e32 v45, v45, v46
	v_add_f32_e32 v44, v44, v45
	v_mul_f32_e32 v45, v65, v65
	v_mul_f32_e32 v46, v49, v49
	v_fmac_f32_e32 v45, v64, v64
	v_fmac_f32_e32 v46, v48, v48
	v_add_f32_e32 v45, v45, v46
	v_add_f32_e32 v44, v45, v44
	v_mul_f32_e32 v45, v67, v67
	v_mul_f32_e32 v46, v51, v51
	v_fmac_f32_e32 v45, v66, v66
	v_fmac_f32_e32 v46, v50, v50
	v_add_f32_e32 v45, v45, v46
	v_add_f32_e32 v44, v45, v44
	v_mul_f32_e32 v45, v69, v69
	v_mul_f32_e32 v46, v53, v53
	v_fmac_f32_e32 v45, v68, v68
	v_fmac_f32_e32 v46, v52, v52
	v_add_f32_e32 v45, v45, v46
	v_add_f32_e32 v44, v45, v44
	v_mul_f32_e32 v45, v71, v71
	v_mul_f32_e32 v46, v55, v55
	v_fmac_f32_e32 v45, v70, v70
	v_fmac_f32_e32 v46, v54, v54
	v_add_f32_e32 v45, v45, v46
	v_add_f32_e32 v44, v45, v44
	v_mul_f32_e32 v45, v73, v73
	v_mul_f32_e32 v46, v57, v57
	v_fmac_f32_e32 v45, v72, v72
	v_fmac_f32_e32 v46, v56, v56
	v_add_f32_e32 v45, v45, v46
	v_add_f32_e32 v44, v45, v44
	v_mul_f32_e32 v45, v75, v75
	v_mul_f32_e32 v46, v59, v59
	v_fmac_f32_e32 v45, v74, v74
	v_fmac_f32_e32 v46, v58, v58
	v_add_f32_e32 v45, v45, v46
	v_add_f32_e32 v44, v45, v44
	s_nop 1
	v_mov_b32_dpp v45, v44 quad_perm:[1,0,3,2] row_mask:0xf bank_mask:0xf
	v_bfe_u32 v46, v73, 16, 1
	v_lshrrev_b32_e32 v43, 16, v43
	v_add3_u32 v46, v73, v46, s56
	v_and_or_b32 v46, v46, s82, v43
	v_add_f32_e32 v44, v44, v45
	s_nop 1
	v_mov_b32_dpp v45, v44 quad_perm:[2,3,0,1] row_mask:0xf bank_mask:0xf
	v_bfe_u32 v43, v56, 16, 1
	v_add3_u32 v43, v56, v43, s56
	v_bfe_u32 v47, v57, 16, 1
	v_lshrrev_b32_e32 v43, 16, v43
	v_add_f32_e32 v44, v44, v45
	s_nop 1
	v_mov_b32_dpp v45, v44 row_half_mirror row_mask:0xf bank_mask:0xf
	v_add3_u32 v47, v57, v47, s56
	v_and_or_b32 v47, v47, s82, v43
	v_bfe_u32 v43, v74, 16, 1
	v_add3_u32 v43, v74, v43, s56
	v_add_f32_e32 v44, v44, v45
	s_nop 1
	v_mov_b32_dpp v45, v44 row_mirror row_mask:0xf bank_mask:0xf
	v_bfe_u32 v48, v75, 16, 1
	v_lshrrev_b32_e32 v43, 16, v43
	v_add3_u32 v48, v75, v48, s56
	v_and_or_b32 v48, v48, s82, v43
	v_add_f32_e32 v44, v44, v45
	v_mov_b32_e32 v45, v44
	s_nop 1
	v_permlane16_swap_b32_e32 v44, v45
	v_bfe_u32 v43, v58, 16, 1
	v_add3_u32 v43, v58, v43, s56
	v_lshrrev_b32_e32 v49, 16, v43
	v_add_f32_e32 v43, v44, v45
	v_mov_b32_e32 v44, v43
	s_nop 1
	v_permlane32_swap_b32_e32 v43, v44
	v_bfe_u32 v45, v59, 16, 1
	v_add3_u32 v45, v59, v45, s56
	v_and_or_b32 v49, v45, s82, v49
	global_store_dwordx4 v[34:35], v[46:49], off offset:3072
	s_and_saveexec_b64 s[10:11], s[40:41]
	s_cbranch_execz .LBB0_790
; template <bool HIN_BF16, bool HOUT_BF16>
; __device__ __forceinline__ void norm_rows(const bf16* __restrict__ Y, const void* Hin, void* H, const float* __restrict__ gpost, float* __restrict__ RSout, int gw, int NGW, int lane) {
;     ...
;             const float rs = 1.0f / sqrtf(wave_sum(ss) * (1.0f / DM) + RMS_EPS);
;             if (lane == 0) RSout[m] = rs;
	v_add_f32_e32 v34, v43, v44
	v_fmamk_f32 v34, v34, 0x3a000000, v226
	v_mul_f32_e32 v35, 0x4f800000, v34
	v_cmp_gt_f32_e32 vcc, s93, v34
	s_nop 1
	v_cndmask_b32_e32 v34, v34, v35, vcc
	v_sqrt_f32_e32 v35, v34
	s_nop 0
	v_add_u32_e32 v43, -1, v35
	v_fma_f32 v45, -v43, v35, v34
	v_add_u32_e32 v44, 1, v35
	v_cmp_ge_f32_e64 s[42:43], 0, v45
	s_nop 1
	v_cndmask_b32_e64 v43, v35, v43, s[42:43]
	v_fma_f32 v35, -v44, v35, v34
	v_cmp_lt_f32_e64 s[42:43], 0, v35
	s_nop 1
	v_cndmask_b32_e64 v35, v43, v44, s[42:43]
	v_mul_f32_e32 v43, 0x37800000, v35
	v_cndmask_b32_e32 v35, v35, v43, vcc
	v_cmp_class_f32_e32 vcc, v34, v227
	s_nop 1
	v_cndmask_b32_e32 v34, v35, v34, vcc
	v_div_scale_f32 v35, s[20:21], v34, v34, 1.0
	v_rcp_f32_e32 v43, v35
	s_add_u32 s20, s8, s4
	s_addc_u32 s21, s9, s5
	v_fma_f32 v44, -v35, v43, 1.0
	v_fmac_f32_e32 v43, v44, v43
	v_div_scale_f32 v44, vcc, 1.0, v34, 1.0
	v_mul_f32_e32 v45, v44, v43
	v_fma_f32 v46, -v35, v45, v44
	v_fmac_f32_e32 v45, v46, v43
	v_fma_f32 v35, -v35, v45, v44
	v_div_fmas_f32 v35, v35, v43, v45
	v_div_fixup_f32 v34, v35, v34, 1.0
	global_store_dword v205, v34, s[20:21]
	s_branch .LBB0_790

; template <bool HIN_BF16, bool HOUT_BF16>
; __device__ __forceinline__ void norm_rows(const bf16* __restrict__ Y, const void* Hin, void* H, const float* __restrict__ gpost, float* __restrict__ RSout, int gw, int NGW, int lane) {
;     ...
;     for (int m = m0_; m < me_; m += ms_) {
;         f32x4 h[8];
;         if (HIN_BF16) {
; #pragma unroll
;             for (int j = 0; j < 4; ++j) { const v4u w = *(const v4u*)((const bf16*)Hin + (size_t)m * DM + 512 * j + 8 * lane);
;                 h[2 * j] = (f32x4){bf_lo(w[0]), bf_hi(w[0]), bf_lo(w[1]), bf_hi(w[1])}; h[2 * j + 1] = (f32x4){bf_lo(w[2]), bf_hi(w[2]), bf_lo(w[3]), bf_hi(w[3])}; }
;         } else {
;             const float* hr = (const float*)Hin + (size_t)m * DM + 8 * lane;
; #pragma unroll
;             for (int j = 0; j < 4; ++j) { h[2 * j] = *(const f32x4*)(hr + 512 * j); h[2 * j + 1] = *(const f32x4*)(hr + 512 * j + 4); }
;         }
;         if (Y) {
;             v4u y[4]; float ss = 0.f;
; #pragma unroll
;             for (int j = 0; j < 4; ++j) y[j] = *(const v4u*)(Y + (size_t)m * DM + 512 * j + 8 * lane);
; #pragma unroll
;             for (int j = 0; j < 4; ++j)
; #pragma unroll
;                 for (int e = 0; e < 4; ++e) { const float a = bf_lo(y[j][e]), b = bf_hi(y[j][e]); ss += a * a + b * b; }
.LBB0_797:
	global_load_dwordx4 v[160:163], v[34:35], off offset:-3072
	s_brev_b32 s5, 63
	v_add_co_u32_e32 v62, vcc, s5, v34
	s_add_i32 s4, s4, s80
	global_load_dwordx4 v[164:167], v[34:35], off offset:-2048
	v_addc_co_u32_e32 v63, vcc, -1, v35, vcc
	s_cmp_ge_i32 s4, s96
	global_load_dwordx4 v[168:171], v[34:35], off offset:-1024
	global_load_dwordx4 v[172:175], v[34:35], off
	v_lshl_add_u64 v[34:35], v[34:35], 0, s[18:19]
	global_load_dwordx4 v[50:53], v[62:63], off offset:-3072
	global_load_dwordx4 v[54:57], v[62:63], off offset:-2048
	global_load_dwordx4 v[58:61], v[62:63], off offset:-1024
	s_nop 0
	global_load_dwordx4 v[62:65], v[62:63], off
	s_waitcnt vmcnt(7)
	v_lshlrev_b32_e32 v38, 16, v160
	v_and_b32_e32 v39, 0xffff0000, v160
	v_lshlrev_b32_e32 v42, 16, v161
	v_and_b32_e32 v43, 0xffff0000, v161
	v_lshlrev_b32_e32 v36, 16, v162
	v_and_b32_e32 v37, 0xffff0000, v162
	v_lshlrev_b32_e32 v40, 16, v163
	v_and_b32_e32 v41, 0xffff0000, v163
	s_waitcnt vmcnt(6)
	v_lshlrev_b32_e32 v66, 16, v164
	v_and_b32_e32 v67, 0xffff0000, v164
	v_lshlrev_b32_e32 v68, 16, v165
	v_and_b32_e32 v69, 0xffff0000, v165
	v_lshlrev_b32_e32 v70, 16, v166
	v_and_b32_e32 v71, 0xffff0000, v166
	v_lshlrev_b32_e32 v72, 16, v167
	v_and_b32_e32 v73, 0xffff0000, v167
	s_waitcnt vmcnt(5)
	v_lshlrev_b32_e32 v74, 16, v168
	v_and_b32_e32 v75, 0xffff0000, v168
	v_lshlrev_b32_e32 v76, 16, v169
	v_and_b32_e32 v77, 0xffff0000, v169
	v_lshlrev_b32_e32 v78, 16, v170
	v_and_b32_e32 v79, 0xffff0000, v170
	v_lshlrev_b32_e32 v80, 16, v171
	v_and_b32_e32 v81, 0xffff0000, v171
	s_waitcnt vmcnt(4)
	v_lshlrev_b32_e32 v82, 16, v172
	v_and_b32_e32 v83, 0xffff0000, v172
	v_lshlrev_b32_e32 v84, 16, v173
	v_and_b32_e32 v85, 0xffff0000, v173
	v_lshlrev_b32_e32 v86, 16, v174
	v_and_b32_e32 v87, 0xffff0000, v174
	v_lshlrev_b32_e32 v88, 16, v175
	v_and_b32_e32 v89, 0xffff0000, v175
	s_waitcnt vmcnt(3)
	v_lshlrev_b32_e32 v90, 16, v50
	v_and_b32_e32 v91, 0xffff0000, v50
	v_lshlrev_b32_e32 v50, 16, v51
	v_and_b32_e32 v51, 0xffff0000, v51
	v_mul_f32_e32 v92, v91, v91
	v_mul_f32_e32 v93, v51, v51
	v_fmac_f32_e32 v92, v90, v90
	v_fmac_f32_e32 v93, v50, v50
	v_add_f32_e32 v94, v92, v93
	v_and_b32_e32 v93, 0xffff0000, v52
	v_lshlrev_b32_e32 v92, 16, v52
	v_mul_f32_e32 v52, v93, v93
	v_fmac_f32_e32 v52, v92, v92
	v_and_b32_e32 v95, 0xffff0000, v53
	v_add_f32_e32 v52, v52, v94
	v_lshlrev_b32_e32 v94, 16, v53
	v_mul_f32_e32 v53, v95, v95
	v_fmac_f32_e32 v53, v94, v94
	s_waitcnt vmcnt(2)
	v_and_b32_e32 v97, 0xffff0000, v54
	v_add_f32_e32 v52, v53, v52
	v_lshlrev_b32_e32 v96, 16, v54
	v_mul_f32_e32 v53, v97, v97
	v_fmac_f32_e32 v53, v96, v96
	v_lshlrev_b32_e32 v54, 16, v55
	v_and_b32_e32 v55, 0xffff0000, v55
	v_add_f32_e32 v52, v53, v52
	v_mul_f32_e32 v53, v55, v55
	v_fmac_f32_e32 v53, v54, v54
	v_and_b32_e32 v99, 0xffff0000, v56
	v_add_f32_e32 v52, v53, v52
	v_lshlrev_b32_e32 v98, 16, v56
	v_mul_f32_e32 v53, v99, v99
	v_fmac_f32_e32 v53, v98, v98
	v_lshlrev_b32_e32 v56, 16, v57
	v_and_b32_e32 v57, 0xffff0000, v57
	v_add_f32_e32 v52, v53, v52
	v_mul_f32_e32 v53, v57, v57
	v_fmac_f32_e32 v53, v56, v56
	s_waitcnt vmcnt(1)
	v_and_b32_e32 v101, 0xffff0000, v58
	v_add_f32_e32 v52, v53, v52
	v_lshlrev_b32_e32 v100, 16, v58
	v_mul_f32_e32 v53, v101, v101
	v_fmac_f32_e32 v53, v100, v100
	v_lshlrev_b32_e32 v58, 16, v59
	v_and_b32_e32 v59, 0xffff0000, v59
	v_add_f32_e32 v52, v53, v52
	v_mul_f32_e32 v53, v59, v59
	v_fmac_f32_e32 v53, v58, v58
	v_and_b32_e32 v103, 0xffff0000, v60
	v_add_f32_e32 v52, v53, v52
	v_lshlrev_b32_e32 v102, 16, v60
	v_mul_f32_e32 v53, v103, v103
	v_fmac_f32_e32 v53, v102, v102
	v_and_b32_e32 v105, 0xffff0000, v61
	v_add_f32_e32 v52, v53, v52
	v_lshlrev_b32_e32 v104, 16, v61
	v_mul_f32_e32 v53, v105, v105
	v_fmac_f32_e32 v53, v104, v104
	s_waitcnt vmcnt(0)
; __device__ __forceinline__ unsigned pk2(float lo, float hi) { return f2bf(lo) | (f2bf(hi) << 16); }
; __device__ __forceinline__ float wave_sum(float v) {
; #pragma unroll
;     for (int o = 1; o < 64; o <<= 1) v += __shfl_xor(v, o);
;     return v;
; }
; template <bool HIN_BF16, bool HOUT_BF16>
; __device__ __forceinline__ void norm_rows(const bf16* __restrict__ Y, const void* Hin, void* H, const float* __restrict__ gpost, float* __restrict__ RSout, int gw, int NGW, int lane) {
;     ...
;             const float rs = 1.0f / sqrtf(wave_sum(ss) * (1.0f / DM) + RMS_EPS);
; #pragma unroll
;             for (int j = 0; j < 4; ++j) { const f32x4 g0 = *(const f32x4*)(gpost + 512 * j + 8 * lane), g1 = *(const f32x4*)(gpost + 512 * j + 8 * lane + 4);
;                 f32x4 a = {bf_lo(y[j][0]), bf_hi(y[j][0]), bf_lo(y[j][1]), bf_hi(y[j][1])}, b = {bf_lo(y[j][2]), bf_hi(y[j][2]), bf_lo(y[j][3]), bf_hi(y[j][3])};
;                 h[2 * j] = h[2 * j] + a * g0 * rs; h[2 * j + 1] = h[2 * j + 1] + b * g1 * rs; }
;         }
;         if (HOUT_BF16) {
; #pragma unroll
;             for (int j = 0; j < 4; ++j) { v4u w; w.x = pk2(h[2 * j][0], h[2 * j][1]); w.y = pk2(h[2 * j][2], h[2 * j][3]); w.z = pk2(h[2 * j + 1][0], h[2 * j + 1][1]); w.w = pk2(h[2 * j + 1][2], h[2 * j + 1][3]);
;                 *(v4u*)((bf16*)H + (size_t)m * DM + 512 * j + 8 * lane) = w; }
;         } else { float* ho = (float*)H + (size_t)m * DM + 8 * lane;
; #pragma unroll
;             for (int j = 0; j < 4; ++j) { *(f32x4*)(ho + 512 * j) = h[2 * j]; *(f32x4*)(ho + 512 * j + 4) = h[2 * j + 1]; } }
	v_and_b32_e32 v107, 0xffff0000, v62
	v_add_f32_e32 v52, v53, v52
	v_lshlrev_b32_e32 v106, 16, v62
	v_mul_f32_e32 v53, v107, v107
	v_fmac_f32_e32 v53, v106, v106
	v_and_b32_e32 v109, 0xffff0000, v63
	v_add_f32_e32 v52, v53, v52
	v_lshlrev_b32_e32 v108, 16, v63
	v_mul_f32_e32 v53, v109, v109
	v_fmac_f32_e32 v53, v108, v108
	v_and_b32_e32 v113, 0xffff0000, v65
	v_and_b32_e32 v112, 0xffff0000, v64
	v_add_f32_e32 v60, v53, v52
	v_lshlrev_b32_e32 v111, 16, v65
	v_lshlrev_b32_e32 v110, 16, v64
	v_pk_mul_f32 v[52:53], v[112:113], v[112:113]
	v_pk_mul_f32 v[50:51], v[26:27], v[50:51]
	v_pk_fma_f32 v[52:53], v[110:111], v[110:111], v[52:53]
	v_pk_mul_f32 v[56:57], v[10:11], v[56:57]
	v_add_f32_e32 v52, v52, v60
	v_add_f32_e32 v52, v53, v52
	s_nop 1
	v_mov_b32_dpp v53, v52 quad_perm:[1,0,3,2] row_mask:0xf bank_mask:0xf
	v_pk_mul_f32 v[58:59], v[18:19], v[58:59]
	v_pk_mul_f32 v[64:65], v[14:15], v[104:105]
	v_add_f32_e32 v52, v52, v53
	s_nop 1
	v_mov_b32_dpp v53, v52 quad_perm:[2,3,0,1] row_mask:0xf bank_mask:0xf
	v_add_f32_e32 v52, v52, v53
	s_nop 1
	v_mov_b32_dpp v53, v52 row_half_mirror row_mask:0xf bank_mask:0xf
	v_add_f32_e32 v52, v52, v53
	s_nop 1
	v_mov_b32_dpp v53, v52 row_mirror row_mask:0xf bank_mask:0xf
	v_add_f32_e32 v52, v52, v53
	v_mov_b32_e32 v53, v52
	s_nop 1
	v_permlane16_swap_b32_e32 v52, v53
	v_add_f32_e32 v52, v52, v53
	v_mov_b32_e32 v53, v52
	s_nop 1
	v_permlane32_swap_b32_e32 v52, v53
	v_add_f32_e32 v52, v52, v53
	v_fmamk_f32 v52, v52, 0x3a000000, v226
	v_cmp_gt_f32_e32 vcc, s93, v52
	v_mul_f32_e32 v53, 0x4f800000, v52
	s_nop 0
	v_cndmask_b32_e32 v52, v52, v53, vcc
	v_sqrt_f32_e32 v53, v52
	s_nop 0
	v_add_u32_e32 v60, -1, v53
	v_fma_f32 v61, -v60, v53, v52
	v_cmp_ge_f32_e64 s[38:39], 0, v61
	v_add_u32_e32 v61, 1, v53
	s_nop 0
	v_cndmask_b32_e64 v60, v53, v60, s[38:39]
	v_fma_f32 v53, -v61, v53, v52
	v_cmp_lt_f32_e64 s[38:39], 0, v53
	s_nop 1
	v_cndmask_b32_e64 v53, v60, v61, s[38:39]
	v_mul_f32_e32 v60, 0x37800000, v53
	v_cndmask_b32_e32 v53, v53, v60, vcc
	v_cmp_class_f32_e32 vcc, v52, v227
	s_nop 1
	v_cndmask_b32_e32 v52, v53, v52, vcc
	v_div_scale_f32 v53, s[6:7], v52, v52, 1.0
	v_rcp_f32_e32 v60, v53
	s_nop 0
	v_fma_f32 v61, -v53, v60, 1.0
	v_fmac_f32_e32 v60, v61, v60
	v_div_scale_f32 v61, vcc, 1.0, v52, 1.0
	v_mul_f32_e32 v62, v61, v60
	v_fma_f32 v63, -v53, v62, v61
	v_fmac_f32_e32 v62, v63, v60
	v_fma_f32 v53, -v53, v62, v61
	v_div_fmas_f32 v53, v53, v60, v62
	v_div_fixup_f32 v114, v53, v52, 1.0
	v_pk_mul_f32 v[60:61], v[24:25], v[90:91]
	v_pk_fma_f32 v[52:53], v[50:51], v[114:115], v[42:43] op_sel_hi:[1,0,1]
	v_pk_mul_f32 v[42:43], v[0:1], v[92:93]
	v_pk_fma_f32 v[50:51], v[60:61], v[114:115], v[38:39] op_sel_hi:[1,0,1]
	v_pk_mul_f32 v[38:39], v[2:3], v[94:95]
	v_pk_fma_f32 v[36:37], v[42:43], v[114:115], v[36:37] op_sel_hi:[1,0,1]
	v_pk_mul_f32 v[42:43], v[6:7], v[54:55]
	v_pk_mul_f32 v[54:55], v[8:9], v[98:99]
	v_pk_fma_f32 v[38:39], v[38:39], v[114:115], v[40:41] op_sel_hi:[1,0,1]
	v_pk_mul_f32 v[40:41], v[4:5], v[96:97]
	v_pk_fma_f32 v[54:55], v[54:55], v[114:115], v[70:71] op_sel_hi:[1,0,1]
	v_pk_mul_f32 v[62:63], v[16:17], v[100:101]
	v_mov_b32_e32 v70, v110
	v_mov_b32_e32 v71, v112
	v_mov_b32_e32 v112, v111
	v_pk_fma_f32 v[42:43], v[42:43], v[114:115], v[68:69] op_sel_hi:[1,0,1]
	v_pk_fma_f32 v[40:41], v[40:41], v[114:115], v[66:67] op_sel_hi:[1,0,1]
	v_pk_fma_f32 v[56:57], v[56:57], v[114:115], v[72:73] op_sel_hi:[1,0,1]
	v_pk_fma_f32 v[60:61], v[58:59], v[114:115], v[76:77] op_sel_hi:[1,0,1]
	v_pk_fma_f32 v[58:59], v[62:63], v[114:115], v[74:75] op_sel_hi:[1,0,1]
	v_pk_mul_f32 v[62:63], v[12:13], v[102:103]
	v_pk_mul_f32 v[66:67], v[20:21], v[106:107]
	v_pk_mul_f32 v[68:69], v[22:23], v[108:109]
	v_pk_mul_f32 v[70:71], v[28:29], v[70:71]
	v_pk_mul_f32 v[72:73], v[30:31], v[112:113]
	v_pk_fma_f32 v[64:65], v[64:65], v[114:115], v[80:81] op_sel_hi:[1,0,1]
	v_pk_fma_f32 v[62:63], v[62:63], v[114:115], v[78:79] op_sel_hi:[1,0,1]
	v_pk_fma_f32 v[68:69], v[68:69], v[114:115], v[84:85] op_sel_hi:[1,0,1]
	v_pk_fma_f32 v[66:67], v[66:67], v[114:115], v[82:83] op_sel_hi:[1,0,1]
	v_pk_fma_f32 v[72:73], v[72:73], v[114:115], v[88:89] op_sel_hi:[1,0,1]
	v_pk_fma_f32 v[70:71], v[70:71], v[114:115], v[86:87] op_sel_hi:[1,0,1]
	global_store_dwordx4 v[32:33], v[50:53], off offset:-4096
	global_store_dwordx4 v[32:33], v[36:39], off offset:-4080
	global_store_dwordx4 v[32:33], v[40:43], off offset:-2048
	global_store_dwordx4 v[32:33], v[54:57], off offset:-2032
	global_store_dwordx4 v[32:33], v[58:61], off
	global_store_dwordx4 v[32:33], v[62:65], off offset:16
	global_store_dwordx4 v[32:33], v[66:69], off offset:2048
	global_store_dwordx4 v[32:33], v[70:73], off offset:2064
	v_lshl_add_u64 v[32:33], v[32:33], 0, s[22:23]
	s_cbranch_scc0 .LBB0_797
